# v28 + acquire buffer_inv issued right after the arrive (overlapped with the first poll) in the five same-XCD row-panel syncs; cross-XCD path unchanged
# baseline (speedup 1.0000x reference)
.LBB0_419:
	s_or_b64 exec, exec, s[8:9]
	v_mov_b32_e32 v0, 0
	v_readlane_b32 s98, v251, 24
	s_cmp_lg_u32 s98, 0
	s_cbranch_scc1 .Lei_a1
	buffer_inv sc1
.Lei_a1:
	global_load_dword v1, v0, s[4:5] sc1
	s_waitcnt vmcnt(0)
	v_cmp_lt_u32_e32 vcc, 3, v1
	s_cbranch_vccnz .LBB0_432
	s_mov_b32 s14, 1
	s_branch .LBB0_422

.LBB0_432:
	s_waitcnt vmcnt(0)
	s_cmp_eq_u32 s98, 0
	s_cbranch_scc1 .Lei_b1
	buffer_inv sc1
.Lei_b1:
	s_waitcnt vmcnt(0)
.LBB0_433:
	s_or_b64 exec, exec, s[0:1]

.LBB0_461:
	s_or_b64 exec, exec, s[12:13]
	v_mov_b32_e32 v0, 0
	v_readlane_b32 s98, v251, 24
	s_cmp_lg_u32 s98, 0
	s_cbranch_scc1 .Lei_a2
	buffer_inv sc1
.Lei_a2:
	global_load_dword v1, v0, s[8:9] sc1
	s_waitcnt vmcnt(0)
	v_cmp_lt_u32_e32 vcc, 3, v1
	s_cbranch_vccnz .LBB0_474
	s_add_u32 s10, s54, 0x4200
	s_addc_u32 s11, s55, 0
	s_mov_b32 s14, 1
	s_branch .LBB0_464

.Lei_b2:
	s_waitcnt vmcnt(0)
.LBB0_475:
	s_or_b64 exec, exec, s[6:7]

.Lei_b3:
	s_waitcnt vmcnt(0)
.LBB0_548:
	s_or_b64 exec, exec, s[6:7]

.Lei_b4:
	s_waitcnt vmcnt(0)
.LBB0_596:
	s_or_b64 exec, exec, s[6:7]

.Lei_a5:
	global_load_dword v1, v0, s[4:5] sc1
	s_waitcnt vmcnt(0)
	v_cmp_lt_u32_e32 vcc, 3, v1
	s_cbranch_vccnz .LBB0_657
	s_add_u32 s6, s54, 0x4200
	s_addc_u32 s7, s55, 0
	s_mov_b32 s15, 1
	s_branch .LBB0_647

.Lei_b5:
	s_waitcnt vmcnt(0)
.LBB0_658:
	s_or_b64 exec, exec, s[2:3]
